# v75 with the phase-1 tail share of compressed-KV pages spread over workgroups >= 140 instead of >= 180 (work partition tuning)
# speedup vs baseline: 1.0090x; 1.0077x over previous
.LBB0_7:
	s_nop 0
	v_readlane_b32 s0, v254, 2
	v_readlane_b32 s1, v254, 3
	v_writelane_b32 v254, s48, 40
	s_cmp_lt_i32 s0, 1
	s_cselect_b64 s[4:5], -1, 0
	v_writelane_b32 v254, s49, 41
	v_writelane_b32 v254, s50, 42
	s_cmp_gt_i32 s1, 0
	v_writelane_b32 v254, s51, 43
	s_cselect_b64 s[6:7], -1, 0
	v_writelane_b32 v254, s52, 44
	s_and_b64 s[6:7], s[4:5], s[6:7]
	v_writelane_b32 v254, s53, 45
	s_andn2_b64 vcc, exec, s[6:7]
	v_and_b32_e32 v206, 63, v0
	v_writelane_b32 v254, s54, 46
	v_writelane_b32 v254, s55, 47
	s_cbranch_vccnz .LBB0_113
	s_movk_i32 s98, 0x2a7f
	v_readlane_b32 s0, v254, 0
	v_readlane_b32 s1, v254, 1
	s_load_dword s8, s[0:1], 0xe8
	v_readfirstlane_b32 s0, v0
	s_lshr_b32 s9, s0, 6
	s_lshl_b32 s0, s2, 3
	s_add_i32 s10, s9, s0
	s_waitcnt lgkmcnt(0)
	s_cmp_le_u32 s8, 140
	s_cbranch_scc1 .Lrc_nb
	s_sub_u32 s0, s8, 140
	s_lshl_b32 s0, s0, 3
	s_sub_u32 s98, s98, s0

.LBB0_325:
	s_cmp_eq_u32 s99, 5
	s_cbranch_scc0 .Lrc_p1skip
	s_cmp_lt_u32 s100, 140
	s_cbranch_scc1 .Lrc_p1skip
	s_mov_b32 s99, 7
	s_mov_b64 exec, -1
	v_readlane_b32 s0, v254, 0
	v_readlane_b32 s1, v254, 1
	v_readlane_b32 s52, v254, 44
	v_readlane_b32 s53, v254, 45
	v_readlane_b32 s54, v254, 46
	v_readlane_b32 s55, v254, 47
	s_nop 4
	s_load_dwordx16 s[76:91], s[0:1], 0x0
	s_load_dword s8, s[0:1], 0xe8
	s_waitcnt lgkmcnt(0)
	s_add_u32 s2, s100, 0x550
	s_sub_u32 s2, s2, s8
	s_sub_u32 s8, s8, 140
	s_movk_i32 s98, 0x2a7f
	v_readfirstlane_b32 s9, v0
	s_lshr_b32 s9, s9, 6
	s_lshl_b32 s10, s2, 3
	s_add_u32 s10, s10, s9
	s_lshl_b32 s3, s8, 3
	v_and_b32_e32 v34, 63, v0
	s_branch .LBB0_78
